# SSD prefetch no longer drained at issue; finer MFMA-VALU interleave in attention
# speedup vs baseline: 1.0382x; 1.0025x over previous
; __device__ __forceinline__ void attn_unit(CArgs a, int layer, int unit, LAS unsigned char* lds) {
;     ...
;     auto qk = [&](int buf, f32x16& p0, f32x16& p1) {
;         const LAS bf16_t* Kl = (const LAS bf16_t*)(lds + AT_K + buf * AT_KB);
; #pragma unroll
;         for (int s = 0; s < 6; ++s) {
;             const bf16x8 k0 = *(const LAS bf16x8*)(Kl + r32 * AT_KLD + 16 * s + 8 * hi);
;             const bf16x8 k1 = *(const LAS bf16x8*)(Kl + (32 + r32) * AT_KLD + 16 * s + 8 * hi);
;             if (s == 0) { p0 = MFMA32(k0, qf[0], negm); p1 = MFMA32(k1, qf[0], negm); }
;             else { p0 = MFMA32(k0, qf[s], p0); p1 = MFMA32(k1, qf[s], p1); }
;         }
;     };
;     __syncthreads();
;     gloadK(0); gloadV(0); lstoreK(0); lstoreV(0); gloadK(1); lstoreK(1);
;     __syncthreads();
;     float lrun = 0.f;
;     f32x16 o0, o1, pA0, pA1, pB0, pB1;
; #pragma unroll
;     for (int r = 0; r < 16; ++r) { o0[r] = 0.f; o1[r] = 0.f; }
;     qk(0, pA0, pA1);
;     auto tile = [&](int t, f32x16& c0, f32x16& c1, f32x16& n0, f32x16& n1) {
;         const int buf = t & 1;
;         gloadK(t + 2 < NT ? t + 2 : NT - 1); gloadV(t + 1 < NT ? t + 1 : NT - 1);
;         const LAS bf16_t* Vl = (const LAS bf16_t*)(lds + AT_V + buf * AT_VB);
;         if (t + 1 < NT) qk(buf ^ 1, n0, n1);
;         f32x16 p0, p1;
;         float rs = 0.f;
; #pragma unroll
;         for (int r = 0; r < 16; ++r) { p0[r] = __builtin_amdgcn_exp2f(c0[r]); p1[r] = __builtin_amdgcn_exp2f(c1[r]); rs += p0[r] + p1[r]; }
;         lrun += rs;
;         bf16x8 pf[4];
; #pragma unroll
;         for (int s = 0; s < 2; ++s) {
;             u32x4 w0, w1;
;             w0.x = cvt_pk_bf16(p0[8 * s], p0[8 * s + 1]); w0.y = cvt_pk_bf16(p0[8 * s + 2], p0[8 * s + 3]); w0.z = cvt_pk_bf16(p0[8 * s + 4], p0[8 * s + 5]); w0.w = cvt_pk_bf16(p0[8 * s + 6], p0[8 * s + 7]);
;             w1.x = cvt_pk_bf16(p1[8 * s], p1[8 * s + 1]); w1.y = cvt_pk_bf16(p1[8 * s + 2], p1[8 * s + 3]); w1.z = cvt_pk_bf16(p1[8 * s + 4], p1[8 * s + 5]); w1.w = cvt_pk_bf16(p1[8 * s + 6], p1[8 * s + 7]);
;             pf[s] = __builtin_bit_cast(bf16x8, w0); pf[2 + s] = __builtin_bit_cast(bf16x8, w1);
;         }
; #pragma unroll
;         for (int i = 0; i < 12; ++i) { __builtin_amdgcn_sched_group_barrier(0x008, 1, 0); __builtin_amdgcn_sched_group_barrier(0x002, 9, 0); }
; #pragma unroll
;         for (int s4 = 0; s4 < 4; ++s4) {
.Lattn_loop:
	s_add_i32 s12, s13, 3
	s_min_u32 s12, s12, 31
	s_mul_i32 s12, s12, 0x3000
	s_add_u32 s2, s20, s12
	s_addc_u32 s3, s21, 0
	s_add_i32 s12, s13, 2
	s_min_u32 s12, s12, 31
	s_lshl_b32 s12, s12, 13
	s_add_u32 s24, s18, s12
	s_addc_u32 s25, s19, 0
	global_load_dwordx4 v[200:203], v152, s[2:3]
	global_load_dwordx4 v[204:207], v175, s[2:3]
	global_load_dwordx4 v[208:211], v152, s[24:25]
	ds_read_b128 v[138:141], v168 offset:13312
	ds_read_b128 v[142:145], v168 offset:19968
	ds_read_b128 v[146:149], v168 offset:13344
	ds_read_b64_tr_b16 v[212:213], v170 offset:26624
	ds_read_b64_tr_b16 v[214:215], v170 offset:27776
	ds_read_b64_tr_b16 v[216:217], v170 offset:26688
	ds_read_b64_tr_b16 v[218:219], v170 offset:27840
	v_exp_f32_e32 v192, v50
	v_exp_f32_e32 v193, v51
	v_exp_f32_e32 v194, v52
	v_exp_f32_e32 v195, v53
	v_exp_f32_e32 v196, v54
	v_exp_f32_e32 v197, v55
	s_waitcnt lgkmcnt(6)
	v_mfma_f32_32x32x16_bf16 v[98:113], v[138:141], v[114:117], v[34:49]
	ds_read_b128 v[138:141], v168 offset:20000
	v_exp_f32_e32 v198, v56
	v_exp_f32_e32 v199, v57
	v_add_f32_e32 v173, v192, v193
	v_add_f32_e32 v174, v194, v195
	v_add_f32_e32 v173, v173, v196
	v_add_f32_e32 v174, v174, v197
	s_waitcnt lgkmcnt(6)
	v_mfma_f32_32x32x16_bf16 v[82:97], v[142:145], v[114:117], v[34:49]
	ds_read_b128 v[142:145], v168 offset:13376
	v_add_f32_e32 v173, v173, v198
	v_add_f32_e32 v174, v174, v199
	v_cvt_pk_bf16_f32 v176, v192, v193
	v_cvt_pk_bf16_f32 v177, v194, v195
	v_cvt_pk_bf16_f32 v178, v196, v197
	v_cvt_pk_bf16_f32 v179, v198, v199
	s_waitcnt lgkmcnt(6)
	v_mfma_f32_32x32x16_bf16 v[98:113], v[146:149], v[118:121], v[98:113]
	ds_read_b128 v[146:149], v168 offset:20032
	v_exp_f32_e32 v192, v58
	v_exp_f32_e32 v193, v59
	v_exp_f32_e32 v194, v60
	v_exp_f32_e32 v195, v61
	s_waitcnt lgkmcnt(5)
	v_mfma_f32_32x32x16_bf16 v[2:17], v[176:179], v[212:215], v[2:17]
	ds_read_b64_tr_b16 v[220:221], v170 offset:28928
	ds_read_b64_tr_b16 v[222:223], v170 offset:30080
	v_exp_f32_e32 v196, v62
	v_exp_f32_e32 v197, v63
	v_exp_f32_e32 v198, v64
	v_exp_f32_e32 v199, v65
	s_waitcnt lgkmcnt(5)
	v_mfma_f32_32x32x16_bf16 v[18:33], v[176:179], v[216:219], v[18:33]
	ds_read_b64_tr_b16 v[236:237], v170 offset:28992
	ds_read_b64_tr_b16 v[238:239], v170 offset:30144
	v_add_f32_e32 v173, v173, v192
	v_add_f32_e32 v174, v174, v193
	v_add_f32_e32 v173, v173, v194
	v_add_f32_e32 v174, v174, v195
	s_waitcnt lgkmcnt(6)
	v_mfma_f32_32x32x16_bf16 v[82:97], v[138:141], v[118:121], v[82:97]
	ds_read_b128 v[138:141], v168 offset:13408
	v_add_f32_e32 v173, v173, v196
	v_add_f32_e32 v174, v174, v197
	v_add_f32_e32 v173, v173, v198
	v_add_f32_e32 v174, v174, v199
	s_waitcnt lgkmcnt(6)
	v_mfma_f32_32x32x16_bf16 v[98:113], v[142:145], v[122:125], v[98:113]
	ds_read_b128 v[142:145], v168 offset:20064
	v_cvt_pk_bf16_f32 v180, v192, v193
	v_cvt_pk_bf16_f32 v181, v194, v195
	v_cvt_pk_bf16_f32 v182, v196, v197
	v_cvt_pk_bf16_f32 v183, v198, v199
	s_waitcnt lgkmcnt(6)
	v_mfma_f32_32x32x16_bf16 v[82:97], v[146:149], v[122:125], v[82:97]
	ds_read_b128 v[146:149], v168 offset:13440
	v_exp_f32_e32 v192, v66
	v_exp_f32_e32 v193, v67
	v_exp_f32_e32 v194, v68
	v_exp_f32_e32 v195, v69
	s_waitcnt lgkmcnt(5)
	v_mfma_f32_32x32x16_bf16 v[2:17], v[180:183], v[220:223], v[2:17]
	ds_read_b64_tr_b16 v[212:213], v170 offset:31232
	ds_read_b64_tr_b16 v[214:215], v170 offset:32384
	v_exp_f32_e32 v196, v70
	v_exp_f32_e32 v197, v71
	v_exp_f32_e32 v198, v72
	v_exp_f32_e32 v199, v73
	s_waitcnt lgkmcnt(5)
	v_mfma_f32_32x32x16_bf16 v[18:33], v[180:183], v[236:239], v[18:33]
	ds_read_b64_tr_b16 v[216:217], v170 offset:31296
	ds_read_b64_tr_b16 v[218:219], v170 offset:32448
	v_add_f32_e32 v173, v173, v192
	v_add_f32_e32 v174, v174, v193
	v_add_f32_e32 v173, v173, v194
	v_add_f32_e32 v174, v174, v195
	s_waitcnt lgkmcnt(6)
	v_mfma_f32_32x32x16_bf16 v[98:113], v[138:141], v[126:129], v[98:113]
	ds_read_b128 v[138:141], v168 offset:20096
	v_add_f32_e32 v173, v173, v196
	v_add_f32_e32 v174, v174, v197
	v_add_f32_e32 v173, v173, v198
	v_add_f32_e32 v174, v174, v199
	s_waitcnt lgkmcnt(6)
	v_mfma_f32_32x32x16_bf16 v[82:97], v[142:145], v[126:129], v[82:97]
	ds_read_b128 v[142:145], v168 offset:13472
	v_cvt_pk_bf16_f32 v184, v192, v193
	v_cvt_pk_bf16_f32 v185, v194, v195
	v_cvt_pk_bf16_f32 v186, v196, v197
	v_cvt_pk_bf16_f32 v187, v198, v199
	s_waitcnt lgkmcnt(6)
	v_mfma_f32_32x32x16_bf16 v[98:113], v[146:149], v[130:133], v[98:113]
	ds_read_b128 v[146:149], v168 offset:20128
	v_exp_f32_e32 v192, v74
	v_exp_f32_e32 v193, v75
	v_exp_f32_e32 v194, v76
	v_exp_f32_e32 v195, v77
	s_waitcnt lgkmcnt(5)
	v_mfma_f32_32x32x16_bf16 v[2:17], v[184:187], v[212:215], v[2:17]
	ds_read_b64_tr_b16 v[220:221], v170 offset:33536
	ds_read_b64_tr_b16 v[222:223], v170 offset:34688
	v_exp_f32_e32 v196, v78
	v_exp_f32_e32 v197, v79
	v_exp_f32_e32 v198, v80
	v_exp_f32_e32 v199, v81
	s_waitcnt lgkmcnt(5)
	v_mfma_f32_32x32x16_bf16 v[18:33], v[184:187], v[216:219], v[18:33]
	ds_read_b64_tr_b16 v[236:237], v170 offset:33600
	ds_read_b64_tr_b16 v[238:239], v170 offset:34752
	v_add_f32_e32 v173, v173, v192
	v_add_f32_e32 v174, v174, v193
	v_add_f32_e32 v173, v173, v194
	v_add_f32_e32 v174, v174, v195
	s_waitcnt lgkmcnt(6)
	v_mfma_f32_32x32x16_bf16 v[82:97], v[138:141], v[130:133], v[82:97]
	v_add_f32_e32 v173, v173, v196
	v_add_f32_e32 v174, v174, v197
	v_add_f32_e32 v173, v173, v198
	v_add_f32_e32 v174, v174, v199
	s_waitcnt lgkmcnt(5)
	v_mfma_f32_32x32x16_bf16 v[98:113], v[142:145], v[134:137], v[98:113]
	v_cvt_pk_bf16_f32 v188, v192, v193
	v_cvt_pk_bf16_f32 v189, v194, v195
	v_cvt_pk_bf16_f32 v190, v196, v197
	v_cvt_pk_bf16_f32 v191, v198, v199
	s_waitcnt lgkmcnt(4)
	v_mfma_f32_32x32x16_bf16 v[82:97], v[146:149], v[134:137], v[82:97]
	v_add_f32_e32 v172, v172, v173
	v_add_f32_e32 v172, v172, v174
	s_waitcnt lgkmcnt(2)
	v_mfma_f32_32x32x16_bf16 v[2:17], v[188:191], v[220:223], v[2:17]
	s_waitcnt vmcnt(3)
	ds_write_b128 v166, v[224:227]
	ds_write_b128 v167, v[232:235] offset:35840
	s_waitcnt lgkmcnt(2)
	v_mfma_f32_32x32x16_bf16 v[18:33], v[188:191], v[236:239], v[18:33]
	s_and_b64 vcc, exec, s[40:41]
	s_cbranch_vccz .Lattn_nok1_a
	ds_write_b128 v171, v[228:231]
; __device__ __forceinline__ void attn_unit(CArgs a, int layer, int unit, LAS unsigned char* lds) {
;     ...
;     auto qk = [&](int buf, f32x16& p0, f32x16& p1) {
;         const LAS bf16_t* Kl = (const LAS bf16_t*)(lds + AT_K + buf * AT_KB);
; #pragma unroll
;         for (int s = 0; s < 6; ++s) {
;             const bf16x8 k0 = *(const LAS bf16x8*)(Kl + r32 * AT_KLD + 16 * s + 8 * hi);
;             const bf16x8 k1 = *(const LAS bf16x8*)(Kl + (32 + r32) * AT_KLD + 16 * s + 8 * hi);
;             if (s == 0) { p0 = MFMA32(k0, qf[0], negm); p1 = MFMA32(k1, qf[0], negm); }
;             else { p0 = MFMA32(k0, qf[s], p0); p1 = MFMA32(k1, qf[s], p1); }
;         }
;     };
;     __syncthreads();
;     gloadK(0); gloadV(0); lstoreK(0); lstoreV(0); gloadK(1); lstoreK(1);
;     __syncthreads();
;     float lrun = 0.f;
;     f32x16 o0, o1, pA0, pA1, pB0, pB1;
; #pragma unroll
;     for (int r = 0; r < 16; ++r) { o0[r] = 0.f; o1[r] = 0.f; }
;     qk(0, pA0, pA1);
;     auto tile = [&](int t, f32x16& c0, f32x16& c1, f32x16& n0, f32x16& n1) {
;         const int buf = t & 1;
;         gloadK(t + 2 < NT ? t + 2 : NT - 1); gloadV(t + 1 < NT ? t + 1 : NT - 1);
;         const LAS bf16_t* Vl = (const LAS bf16_t*)(lds + AT_V + buf * AT_VB);
;         if (t + 1 < NT) qk(buf ^ 1, n0, n1);
;         f32x16 p0, p1;
;         float rs = 0.f;
; #pragma unroll
;         for (int r = 0; r < 16; ++r) { p0[r] = __builtin_amdgcn_exp2f(c0[r]); p1[r] = __builtin_amdgcn_exp2f(c1[r]); rs += p0[r] + p1[r]; }
;         lrun += rs;
;         bf16x8 pf[4];
; #pragma unroll
;         for (int s = 0; s < 2; ++s) {
;             u32x4 w0, w1;
;             w0.x = cvt_pk_bf16(p0[8 * s], p0[8 * s + 1]); w0.y = cvt_pk_bf16(p0[8 * s + 2], p0[8 * s + 3]); w0.z = cvt_pk_bf16(p0[8 * s + 4], p0[8 * s + 5]); w0.w = cvt_pk_bf16(p0[8 * s + 6], p0[8 * s + 7]);
;             w1.x = cvt_pk_bf16(p1[8 * s], p1[8 * s + 1]); w1.y = cvt_pk_bf16(p1[8 * s + 2], p1[8 * s + 3]); w1.z = cvt_pk_bf16(p1[8 * s + 4], p1[8 * s + 5]); w1.w = cvt_pk_bf16(p1[8 * s + 6], p1[8 * s + 7]);
;             pf[s] = __builtin_bit_cast(bf16x8, w0); pf[2 + s] = __builtin_bit_cast(bf16x8, w1);
;         }
; #pragma unroll
;         for (int i = 0; i < 12; ++i) { __builtin_amdgcn_sched_group_barrier(0x008, 1, 0); __builtin_amdgcn_sched_group_barrier(0x002, 9, 0); }
; #pragma unroll
;         for (int s4 = 0; s4 < 4; ++s4) {
.Lattn_nok1_a:
	s_waitcnt lgkmcnt(0)
	s_barrier
	s_add_i32 s12, s13, 4
	s_min_u32 s12, s12, 31
	s_mul_i32 s12, s12, 0x3000
	s_add_u32 s2, s20, s12
	s_addc_u32 s3, s21, 0
	s_add_i32 s12, s13, 3
	s_min_u32 s12, s12, 31
	s_lshl_b32 s12, s12, 13
	s_add_u32 s24, s18, s12
	s_addc_u32 s25, s19, 0
	global_load_dwordx4 v[224:227], v152, s[2:3]
	global_load_dwordx4 v[228:231], v175, s[2:3]
	global_load_dwordx4 v[232:235], v152, s[24:25]
	ds_read_b128 v[138:141], v168 offset:0
	ds_read_b128 v[142:145], v168 offset:6656
	ds_read_b128 v[146:149], v168 offset:32
	ds_read_b64_tr_b16 v[212:213], v170 offset:35840
	ds_read_b64_tr_b16 v[214:215], v170 offset:36992
	ds_read_b64_tr_b16 v[216:217], v170 offset:35904
	ds_read_b64_tr_b16 v[218:219], v170 offset:37056
	v_exp_f32_e32 v192, v98
	v_exp_f32_e32 v193, v99
	v_exp_f32_e32 v194, v100
	v_exp_f32_e32 v195, v101
	v_exp_f32_e32 v196, v102
	v_exp_f32_e32 v197, v103
	s_waitcnt lgkmcnt(6)
	v_mfma_f32_32x32x16_bf16 v[50:65], v[138:141], v[114:117], v[34:49]
	ds_read_b128 v[138:141], v168 offset:6688
	v_exp_f32_e32 v198, v104
	v_exp_f32_e32 v199, v105
	v_add_f32_e32 v173, v192, v193
	v_add_f32_e32 v174, v194, v195
	v_add_f32_e32 v173, v173, v196
	v_add_f32_e32 v174, v174, v197
	s_waitcnt lgkmcnt(6)
	v_mfma_f32_32x32x16_bf16 v[66:81], v[142:145], v[114:117], v[34:49]
	ds_read_b128 v[142:145], v168 offset:64
	v_add_f32_e32 v173, v173, v198
	v_add_f32_e32 v174, v174, v199
	v_cvt_pk_bf16_f32 v176, v192, v193
	v_cvt_pk_bf16_f32 v177, v194, v195
	v_cvt_pk_bf16_f32 v178, v196, v197
	v_cvt_pk_bf16_f32 v179, v198, v199
	s_waitcnt lgkmcnt(6)
	v_mfma_f32_32x32x16_bf16 v[50:65], v[146:149], v[118:121], v[50:65]
	ds_read_b128 v[146:149], v168 offset:6720
	v_exp_f32_e32 v192, v106
	v_exp_f32_e32 v193, v107
	v_exp_f32_e32 v194, v108
	v_exp_f32_e32 v195, v109
	s_waitcnt lgkmcnt(5)
	v_mfma_f32_32x32x16_bf16 v[2:17], v[176:179], v[212:215], v[2:17]
	ds_read_b64_tr_b16 v[220:221], v170 offset:38144
	ds_read_b64_tr_b16 v[222:223], v170 offset:39296
	v_exp_f32_e32 v196, v110
	v_exp_f32_e32 v197, v111
	v_exp_f32_e32 v198, v112
	v_exp_f32_e32 v199, v113
	s_waitcnt lgkmcnt(5)
	v_mfma_f32_32x32x16_bf16 v[18:33], v[176:179], v[216:219], v[18:33]
	ds_read_b64_tr_b16 v[236:237], v170 offset:38208
	ds_read_b64_tr_b16 v[238:239], v170 offset:39360
	v_add_f32_e32 v173, v173, v192
	v_add_f32_e32 v174, v174, v193
	v_add_f32_e32 v173, v173, v194
	v_add_f32_e32 v174, v174, v195
	s_waitcnt lgkmcnt(6)
	v_mfma_f32_32x32x16_bf16 v[66:81], v[138:141], v[118:121], v[66:81]
	ds_read_b128 v[138:141], v168 offset:96
	v_add_f32_e32 v173, v173, v196
	v_add_f32_e32 v174, v174, v197
	v_add_f32_e32 v173, v173, v198
	v_add_f32_e32 v174, v174, v199
	s_waitcnt lgkmcnt(6)
	v_mfma_f32_32x32x16_bf16 v[50:65], v[142:145], v[122:125], v[50:65]
	ds_read_b128 v[142:145], v168 offset:6752
	v_cvt_pk_bf16_f32 v180, v192, v193
	v_cvt_pk_bf16_f32 v181, v194, v195
	v_cvt_pk_bf16_f32 v182, v196, v197
	v_cvt_pk_bf16_f32 v183, v198, v199
	s_waitcnt lgkmcnt(6)
	v_mfma_f32_32x32x16_bf16 v[66:81], v[146:149], v[122:125], v[66:81]
	ds_read_b128 v[146:149], v168 offset:128
	v_exp_f32_e32 v192, v82
	v_exp_f32_e32 v193, v83
	v_exp_f32_e32 v194, v84
	v_exp_f32_e32 v195, v85
	s_waitcnt lgkmcnt(5)
	v_mfma_f32_32x32x16_bf16 v[2:17], v[180:183], v[220:223], v[2:17]
	ds_read_b64_tr_b16 v[212:213], v170 offset:40448
	ds_read_b64_tr_b16 v[214:215], v170 offset:41600
	v_exp_f32_e32 v196, v86
	v_exp_f32_e32 v197, v87
	v_exp_f32_e32 v198, v88
	v_exp_f32_e32 v199, v89
	s_waitcnt lgkmcnt(5)
	v_mfma_f32_32x32x16_bf16 v[18:33], v[180:183], v[236:239], v[18:33]
	ds_read_b64_tr_b16 v[216:217], v170 offset:40512
	ds_read_b64_tr_b16 v[218:219], v170 offset:41664
	v_add_f32_e32 v173, v173, v192
	v_add_f32_e32 v174, v174, v193
	v_add_f32_e32 v173, v173, v194
	v_add_f32_e32 v174, v174, v195
	s_waitcnt lgkmcnt(6)
	v_mfma_f32_32x32x16_bf16 v[50:65], v[138:141], v[126:129], v[50:65]
	ds_read_b128 v[138:141], v168 offset:6784
	v_add_f32_e32 v173, v173, v196
	v_add_f32_e32 v174, v174, v197
	v_add_f32_e32 v173, v173, v198
	v_add_f32_e32 v174, v174, v199
	s_waitcnt lgkmcnt(6)
	v_mfma_f32_32x32x16_bf16 v[66:81], v[142:145], v[126:129], v[66:81]
	ds_read_b128 v[142:145], v168 offset:160
	v_cvt_pk_bf16_f32 v184, v192, v193
	v_cvt_pk_bf16_f32 v185, v194, v195
	v_cvt_pk_bf16_f32 v186, v196, v197
	v_cvt_pk_bf16_f32 v187, v198, v199
	s_waitcnt lgkmcnt(6)
	v_mfma_f32_32x32x16_bf16 v[50:65], v[146:149], v[130:133], v[50:65]
	ds_read_b128 v[146:149], v168 offset:6816
	v_exp_f32_e32 v192, v90
	v_exp_f32_e32 v193, v91
	v_exp_f32_e32 v194, v92
	v_exp_f32_e32 v195, v93
	s_waitcnt lgkmcnt(5)
	v_mfma_f32_32x32x16_bf16 v[2:17], v[184:187], v[212:215], v[2:17]
	ds_read_b64_tr_b16 v[220:221], v170 offset:42752
	ds_read_b64_tr_b16 v[222:223], v170 offset:43904
	v_exp_f32_e32 v196, v94
	v_exp_f32_e32 v197, v95
	v_exp_f32_e32 v198, v96
	v_exp_f32_e32 v199, v97
	s_waitcnt lgkmcnt(5)
	v_mfma_f32_32x32x16_bf16 v[18:33], v[184:187], v[216:219], v[18:33]
	ds_read_b64_tr_b16 v[236:237], v170 offset:42816
	ds_read_b64_tr_b16 v[238:239], v170 offset:43968
	v_add_f32_e32 v173, v173, v192
	v_add_f32_e32 v174, v174, v193
	v_add_f32_e32 v173, v173, v194
	v_add_f32_e32 v174, v174, v195
	s_waitcnt lgkmcnt(6)
	v_mfma_f32_32x32x16_bf16 v[66:81], v[138:141], v[130:133], v[66:81]
	v_add_f32_e32 v173, v173, v196
	v_add_f32_e32 v174, v174, v197
	v_add_f32_e32 v173, v173, v198
	v_add_f32_e32 v174, v174, v199
	s_waitcnt lgkmcnt(5)
	v_mfma_f32_32x32x16_bf16 v[50:65], v[142:145], v[134:137], v[50:65]
	v_cvt_pk_bf16_f32 v188, v192, v193
	v_cvt_pk_bf16_f32 v189, v194, v195
	v_cvt_pk_bf16_f32 v190, v196, v197
	v_cvt_pk_bf16_f32 v191, v198, v199
	s_waitcnt lgkmcnt(4)
	v_mfma_f32_32x32x16_bf16 v[66:81], v[146:149], v[134:137], v[66:81]
	v_add_f32_e32 v172, v172, v173
	v_add_f32_e32 v172, v172, v174
	s_waitcnt lgkmcnt(2)
	v_mfma_f32_32x32x16_bf16 v[2:17], v[188:191], v[220:223], v[2:17]
	s_waitcnt vmcnt(3)
	ds_write_b128 v166, v[200:203] offset:13312
	ds_write_b128 v167, v[208:211] offset:26624
	s_waitcnt lgkmcnt(2)
	v_mfma_f32_32x32x16_bf16 v[18:33], v[188:191], v[236:239], v[18:33]
	s_and_b64 vcc, exec, s[40:41]
	s_cbranch_vccz .Lattn_nok1_b
	ds_write_b128 v171, v[204:207] offset:13312
; __device__ __forceinline__ void attn_unit(CArgs a, int layer, int unit, LAS unsigned char* lds) {
;     ...
;     auto tile = [&](int t, f32x16& c0, f32x16& c1, f32x16& n0, f32x16& n1) {
;         const int buf = t & 1;
;         gloadK(t + 2 < NT ? t + 2 : NT - 1); gloadV(t + 1 < NT ? t + 1 : NT - 1);
;         const LAS bf16_t* Vl = (const LAS bf16_t*)(lds + AT_V + buf * AT_VB);
;         if (t + 1 < NT) qk(buf ^ 1, n0, n1);
;         f32x16 p0, p1;
;         float rs = 0.f;
; #pragma unroll
;         for (int r = 0; r < 16; ++r) { p0[r] = __builtin_amdgcn_exp2f(c0[r]); p1[r] = __builtin_amdgcn_exp2f(c1[r]); rs += p0[r] + p1[r]; }
;         lrun += rs;
;         bf16x8 pf[4];
; #pragma unroll
;         for (int s = 0; s < 2; ++s) {
;             u32x4 w0, w1;
;             w0.x = cvt_pk_bf16(p0[8 * s], p0[8 * s + 1]); w0.y = cvt_pk_bf16(p0[8 * s + 2], p0[8 * s + 3]); w0.z = cvt_pk_bf16(p0[8 * s + 4], p0[8 * s + 5]); w0.w = cvt_pk_bf16(p0[8 * s + 6], p0[8 * s + 7]);
;             w1.x = cvt_pk_bf16(p1[8 * s], p1[8 * s + 1]); w1.y = cvt_pk_bf16(p1[8 * s + 2], p1[8 * s + 3]); w1.z = cvt_pk_bf16(p1[8 * s + 4], p1[8 * s + 5]); w1.w = cvt_pk_bf16(p1[8 * s + 6], p1[8 * s + 7]);
;             pf[s] = __builtin_bit_cast(bf16x8, w0); pf[2 + s] = __builtin_bit_cast(bf16x8, w1);
;         }
; #pragma unroll
;         for (int i = 0; i < 12; ++i) { __builtin_amdgcn_sched_group_barrier(0x008, 1, 0); __builtin_amdgcn_sched_group_barrier(0x002, 9, 0); }
; #pragma unroll
;         for (int s4 = 0; s4 < 4; ++s4) {
;             const int kb = 32 * (s4 >> 1) + 16 * (s4 & 1) + 4 * hi;
;             const LAS bf16_t* vrow = Vl + (kb - 4 * hi + 4 * hi + ((lane & 15) >> 2)) * AT_VLD + 16 * ((lane >> 4) & 1) + 4 * (lane & 3);
;             const v4i16_t a0 = __builtin_amdgcn_ds_read_tr16_b64_v4i16((LAS v4i16_t*)(vrow)), a1 = __builtin_amdgcn_ds_read_tr16_b64_v4i16((LAS v4i16_t*)(vrow + 8 * AT_VLD));
;             const v4i16_t c0 = __builtin_amdgcn_ds_read_tr16_b64_v4i16((LAS v4i16_t*)(vrow + 32)), c1 = __builtin_amdgcn_ds_read_tr16_b64_v4i16((LAS v4i16_t*)(vrow + 8 * AT_VLD + 32));
;             const bf16x8 v0 = __builtin_shufflevector(a0, a1, 0, 1, 2, 3, 4, 5, 6, 7), v1 = __builtin_shufflevector(c0, c1, 0, 1, 2, 3, 4, 5, 6, 7);
;             o0 = MFMA32(pf[s4], v0, o0);
;             o1 = MFMA32(pf[s4], v1, o1);
;         }
;         lstoreK(buf); lstoreV(buf ^ 1);
.Lattn_nok1_b:
	s_waitcnt lgkmcnt(0)
	s_barrier
	s_add_i32 s13, s13, 2
	s_cmp_lt_u32 s13, 30
	s_cbranch_scc1 .Lattn_loop
	ds_read_b128 v[138:141], v168 offset:13312
	ds_read_b128 v[142:145], v168 offset:19968
	ds_read_b128 v[146:149], v168 offset:13344
	ds_read_b64_tr_b16 v[212:213], v170 offset:26624
	ds_read_b64_tr_b16 v[214:215], v170 offset:27776
	ds_read_b64_tr_b16 v[216:217], v170 offset:26688
	ds_read_b64_tr_b16 v[218:219], v170 offset:27840
	v_exp_f32_e32 v192, v50
	v_exp_f32_e32 v193, v51
	v_exp_f32_e32 v194, v52
	v_exp_f32_e32 v195, v53
	v_exp_f32_e32 v196, v54
	v_exp_f32_e32 v197, v55
	s_waitcnt lgkmcnt(6)
	v_mfma_f32_32x32x16_bf16 v[98:113], v[138:141], v[114:117], v[34:49]
	ds_read_b128 v[138:141], v168 offset:20000
	v_exp_f32_e32 v198, v56
	v_exp_f32_e32 v199, v57
	v_add_f32_e32 v173, v192, v193
	v_add_f32_e32 v174, v194, v195
	v_add_f32_e32 v173, v173, v196
	v_add_f32_e32 v174, v174, v197
	s_waitcnt lgkmcnt(6)
	v_mfma_f32_32x32x16_bf16 v[82:97], v[142:145], v[114:117], v[34:49]
	ds_read_b128 v[142:145], v168 offset:13376
	v_add_f32_e32 v173, v173, v198
	v_add_f32_e32 v174, v174, v199
	v_cvt_pk_bf16_f32 v176, v192, v193
	v_cvt_pk_bf16_f32 v177, v194, v195
	v_cvt_pk_bf16_f32 v178, v196, v197
	v_cvt_pk_bf16_f32 v179, v198, v199
	s_waitcnt lgkmcnt(6)
	v_mfma_f32_32x32x16_bf16 v[98:113], v[146:149], v[118:121], v[98:113]
	ds_read_b128 v[146:149], v168 offset:20032
	v_exp_f32_e32 v192, v58
	v_exp_f32_e32 v193, v59
	v_exp_f32_e32 v194, v60
	v_exp_f32_e32 v195, v61
	s_waitcnt lgkmcnt(5)
	v_mfma_f32_32x32x16_bf16 v[2:17], v[176:179], v[212:215], v[2:17]
	ds_read_b64_tr_b16 v[220:221], v170 offset:28928
	ds_read_b64_tr_b16 v[222:223], v170 offset:30080
	v_exp_f32_e32 v196, v62
	v_exp_f32_e32 v197, v63
	v_exp_f32_e32 v198, v64
	v_exp_f32_e32 v199, v65
	s_waitcnt lgkmcnt(5)
	v_mfma_f32_32x32x16_bf16 v[18:33], v[176:179], v[216:219], v[18:33]
	ds_read_b64_tr_b16 v[236:237], v170 offset:28992
	ds_read_b64_tr_b16 v[238:239], v170 offset:30144
	v_add_f32_e32 v173, v173, v192
	v_add_f32_e32 v174, v174, v193
	v_add_f32_e32 v173, v173, v194
	v_add_f32_e32 v174, v174, v195
	s_waitcnt lgkmcnt(6)
	v_mfma_f32_32x32x16_bf16 v[82:97], v[138:141], v[118:121], v[82:97]
	ds_read_b128 v[138:141], v168 offset:13408
	v_add_f32_e32 v173, v173, v196
	v_add_f32_e32 v174, v174, v197
	v_add_f32_e32 v173, v173, v198
	v_add_f32_e32 v174, v174, v199
	s_waitcnt lgkmcnt(6)
	v_mfma_f32_32x32x16_bf16 v[98:113], v[142:145], v[122:125], v[98:113]
	ds_read_b128 v[142:145], v168 offset:20064
	v_cvt_pk_bf16_f32 v180, v192, v193
	v_cvt_pk_bf16_f32 v181, v194, v195
	v_cvt_pk_bf16_f32 v182, v196, v197
	v_cvt_pk_bf16_f32 v183, v198, v199
	s_waitcnt lgkmcnt(6)
	v_mfma_f32_32x32x16_bf16 v[82:97], v[146:149], v[122:125], v[82:97]
	ds_read_b128 v[146:149], v168 offset:13440
	v_exp_f32_e32 v192, v66
	v_exp_f32_e32 v193, v67
	v_exp_f32_e32 v194, v68
	v_exp_f32_e32 v195, v69
	s_waitcnt lgkmcnt(5)
	v_mfma_f32_32x32x16_bf16 v[2:17], v[180:183], v[220:223], v[2:17]
	ds_read_b64_tr_b16 v[212:213], v170 offset:31232
	ds_read_b64_tr_b16 v[214:215], v170 offset:32384
	v_exp_f32_e32 v196, v70
	v_exp_f32_e32 v197, v71
	v_exp_f32_e32 v198, v72
	v_exp_f32_e32 v199, v73
	s_waitcnt lgkmcnt(5)
	v_mfma_f32_32x32x16_bf16 v[18:33], v[180:183], v[236:239], v[18:33]
	ds_read_b64_tr_b16 v[216:217], v170 offset:31296
	ds_read_b64_tr_b16 v[218:219], v170 offset:32448
	v_add_f32_e32 v173, v173, v192
	v_add_f32_e32 v174, v174, v193
	v_add_f32_e32 v173, v173, v194
	v_add_f32_e32 v174, v174, v195
	s_waitcnt lgkmcnt(6)
	v_mfma_f32_32x32x16_bf16 v[98:113], v[138:141], v[126:129], v[98:113]
	ds_read_b128 v[138:141], v168 offset:20096
	v_add_f32_e32 v173, v173, v196
	v_add_f32_e32 v174, v174, v197
	v_add_f32_e32 v173, v173, v198
	v_add_f32_e32 v174, v174, v199
	s_waitcnt lgkmcnt(6)
	v_mfma_f32_32x32x16_bf16 v[82:97], v[142:145], v[126:129], v[82:97]
	ds_read_b128 v[142:145], v168 offset:13472
	v_cvt_pk_bf16_f32 v184, v192, v193
	v_cvt_pk_bf16_f32 v185, v194, v195
	v_cvt_pk_bf16_f32 v186, v196, v197
	v_cvt_pk_bf16_f32 v187, v198, v199
	s_waitcnt lgkmcnt(6)
	v_mfma_f32_32x32x16_bf16 v[98:113], v[146:149], v[130:133], v[98:113]
	ds_read_b128 v[146:149], v168 offset:20128
	v_exp_f32_e32 v192, v74
	v_exp_f32_e32 v193, v75
	v_exp_f32_e32 v194, v76
	v_exp_f32_e32 v195, v77
	s_waitcnt lgkmcnt(5)
	v_mfma_f32_32x32x16_bf16 v[2:17], v[184:187], v[212:215], v[2:17]
	ds_read_b64_tr_b16 v[220:221], v170 offset:33536
	ds_read_b64_tr_b16 v[222:223], v170 offset:34688
	v_exp_f32_e32 v196, v78
	v_exp_f32_e32 v197, v79
	v_exp_f32_e32 v198, v80
	v_exp_f32_e32 v199, v81
	s_waitcnt lgkmcnt(5)
	v_mfma_f32_32x32x16_bf16 v[18:33], v[184:187], v[216:219], v[18:33]
	ds_read_b64_tr_b16 v[236:237], v170 offset:33600
	ds_read_b64_tr_b16 v[238:239], v170 offset:34752
	v_add_f32_e32 v173, v173, v192
	v_add_f32_e32 v174, v174, v193
	v_add_f32_e32 v173, v173, v194
	v_add_f32_e32 v174, v174, v195
	s_waitcnt lgkmcnt(6)
	v_mfma_f32_32x32x16_bf16 v[82:97], v[138:141], v[130:133], v[82:97]
	v_add_f32_e32 v173, v173, v196
	v_add_f32_e32 v174, v174, v197
	v_add_f32_e32 v173, v173, v198
	v_add_f32_e32 v174, v174, v199
	s_waitcnt lgkmcnt(5)
	v_mfma_f32_32x32x16_bf16 v[98:113], v[142:145], v[134:137], v[98:113]
	v_cvt_pk_bf16_f32 v188, v192, v193
	v_cvt_pk_bf16_f32 v189, v194, v195
	v_cvt_pk_bf16_f32 v190, v196, v197
	v_cvt_pk_bf16_f32 v191, v198, v199
	s_waitcnt lgkmcnt(4)
	v_mfma_f32_32x32x16_bf16 v[82:97], v[146:149], v[134:137], v[82:97]
	v_add_f32_e32 v172, v172, v173
	v_add_f32_e32 v172, v172, v174
	s_waitcnt lgkmcnt(2)
	v_mfma_f32_32x32x16_bf16 v[2:17], v[188:191], v[220:223], v[2:17]
	s_waitcnt vmcnt(0)
	ds_write_b128 v166, v[224:227]
	ds_write_b128 v167, v[232:235] offset:35840
	s_waitcnt lgkmcnt(2)
	v_mfma_f32_32x32x16_bf16 v[18:33], v[188:191], v[236:239], v[18:33]
	s_and_b64 vcc, exec, s[40:41]
	s_cbranch_vccz .Lattn_nok1_c
	ds_write_b128 v171, v[228:231]
; __device__ __forceinline__ void attn_unit(CArgs a, int layer, int unit, LAS unsigned char* lds) {
;     ...
;     auto tile = [&](int t, f32x16& c0, f32x16& c1, f32x16& n0, f32x16& n1) {
;         const int buf = t & 1;
;         gloadK(t + 2 < NT ? t + 2 : NT - 1); gloadV(t + 1 < NT ? t + 1 : NT - 1);
;         const LAS bf16_t* Vl = (const LAS bf16_t*)(lds + AT_V + buf * AT_VB);
;         if (t + 1 < NT) qk(buf ^ 1, n0, n1);
;         f32x16 p0, p1;
;         float rs = 0.f;
; #pragma unroll
;         for (int r = 0; r < 16; ++r) { p0[r] = __builtin_amdgcn_exp2f(c0[r]); p1[r] = __builtin_amdgcn_exp2f(c1[r]); rs += p0[r] + p1[r]; }
;         lrun += rs;
;         bf16x8 pf[4];
; #pragma unroll
;         for (int s = 0; s < 2; ++s) {
;             u32x4 w0, w1;
;             w0.x = cvt_pk_bf16(p0[8 * s], p0[8 * s + 1]); w0.y = cvt_pk_bf16(p0[8 * s + 2], p0[8 * s + 3]); w0.z = cvt_pk_bf16(p0[8 * s + 4], p0[8 * s + 5]); w0.w = cvt_pk_bf16(p0[8 * s + 6], p0[8 * s + 7]);
;             w1.x = cvt_pk_bf16(p1[8 * s], p1[8 * s + 1]); w1.y = cvt_pk_bf16(p1[8 * s + 2], p1[8 * s + 3]); w1.z = cvt_pk_bf16(p1[8 * s + 4], p1[8 * s + 5]); w1.w = cvt_pk_bf16(p1[8 * s + 6], p1[8 * s + 7]);
;             pf[s] = __builtin_bit_cast(bf16x8, w0); pf[2 + s] = __builtin_bit_cast(bf16x8, w1);
;         }
; #pragma unroll
;         for (int i = 0; i < 12; ++i) { __builtin_amdgcn_sched_group_barrier(0x008, 1, 0); __builtin_amdgcn_sched_group_barrier(0x002, 9, 0); }
; #pragma unroll
;         for (int s4 = 0; s4 < 4; ++s4) {
;             const int kb = 32 * (s4 >> 1) + 16 * (s4 & 1) + 4 * hi;
;             const LAS bf16_t* vrow = Vl + (kb - 4 * hi + 4 * hi + ((lane & 15) >> 2)) * AT_VLD + 16 * ((lane >> 4) & 1) + 4 * (lane & 3);
;             const v4i16_t a0 = __builtin_amdgcn_ds_read_tr16_b64_v4i16((LAS v4i16_t*)(vrow)), a1 = __builtin_amdgcn_ds_read_tr16_b64_v4i16((LAS v4i16_t*)(vrow + 8 * AT_VLD));
;             const v4i16_t c0 = __builtin_amdgcn_ds_read_tr16_b64_v4i16((LAS v4i16_t*)(vrow + 32)), c1 = __builtin_amdgcn_ds_read_tr16_b64_v4i16((LAS v4i16_t*)(vrow + 8 * AT_VLD + 32));
;             const bf16x8 v0 = __builtin_shufflevector(a0, a1, 0, 1, 2, 3, 4, 5, 6, 7), v1 = __builtin_shufflevector(c0, c1, 0, 1, 2, 3, 4, 5, 6, 7);
;             o0 = MFMA32(pf[s4], v0, o0);
;             o1 = MFMA32(pf[s4], v1, o1);
;         }
;         lstoreK(buf); lstoreV(buf ^ 1);
.Lattn_nok1_c:
	s_waitcnt lgkmcnt(0)
	s_barrier
	ds_read_b64_tr_b16 v[212:213], v170 offset:35840
	ds_read_b64_tr_b16 v[214:215], v170 offset:36992
	ds_read_b64_tr_b16 v[216:217], v170 offset:35904
	ds_read_b64_tr_b16 v[218:219], v170 offset:37056
	v_exp_f32_e32 v192, v98
	v_exp_f32_e32 v193, v99
	v_exp_f32_e32 v194, v100
	v_exp_f32_e32 v195, v101
	v_exp_f32_e32 v196, v102
	v_exp_f32_e32 v197, v103
	v_exp_f32_e32 v198, v104
	v_exp_f32_e32 v199, v105
	v_add_f32_e32 v173, v192, v193
	v_add_f32_e32 v174, v194, v195
	v_add_f32_e32 v173, v173, v196
	v_add_f32_e32 v174, v174, v197
	v_add_f32_e32 v173, v173, v198
	v_add_f32_e32 v174, v174, v199
	v_cvt_pk_bf16_f32 v176, v192, v193
	v_cvt_pk_bf16_f32 v177, v194, v195
	v_cvt_pk_bf16_f32 v178, v196, v197
	v_cvt_pk_bf16_f32 v179, v198, v199
	v_exp_f32_e32 v192, v106
	v_exp_f32_e32 v193, v107
	v_exp_f32_e32 v194, v108
	v_exp_f32_e32 v195, v109
	v_exp_f32_e32 v196, v110
	v_exp_f32_e32 v197, v111
	v_exp_f32_e32 v198, v112
	v_exp_f32_e32 v199, v113
	v_add_f32_e32 v173, v173, v192
	v_add_f32_e32 v174, v174, v193
	s_waitcnt lgkmcnt(2)
	v_mfma_f32_32x32x16_bf16 v[2:17], v[176:179], v[212:215], v[2:17]
	ds_read_b64_tr_b16 v[220:221], v170 offset:38144
	ds_read_b64_tr_b16 v[222:223], v170 offset:39296
	v_add_f32_e32 v173, v173, v194
	v_add_f32_e32 v174, v174, v195
	v_add_f32_e32 v173, v173, v196
	v_add_f32_e32 v174, v174, v197
	v_add_f32_e32 v173, v173, v198
	v_add_f32_e32 v174, v174, v199
	v_cvt_pk_bf16_f32 v180, v192, v193
	v_cvt_pk_bf16_f32 v181, v194, v195
	v_cvt_pk_bf16_f32 v182, v196, v197
	v_cvt_pk_bf16_f32 v183, v198, v199
	s_waitcnt lgkmcnt(2)
	v_mfma_f32_32x32x16_bf16 v[18:33], v[176:179], v[216:219], v[18:33]
	ds_read_b64_tr_b16 v[236:237], v170 offset:38208
	ds_read_b64_tr_b16 v[238:239], v170 offset:39360
	v_exp_f32_e32 v192, v82
	v_exp_f32_e32 v193, v83
	v_exp_f32_e32 v194, v84
	v_exp_f32_e32 v195, v85
	v_exp_f32_e32 v196, v86
	v_exp_f32_e32 v197, v87
	v_exp_f32_e32 v198, v88
	v_exp_f32_e32 v199, v89
	v_add_f32_e32 v173, v173, v192
	v_add_f32_e32 v174, v174, v193
	s_waitcnt lgkmcnt(2)
	v_mfma_f32_32x32x16_bf16 v[2:17], v[180:183], v[220:223], v[2:17]
	ds_read_b64_tr_b16 v[212:213], v170 offset:40448
	ds_read_b64_tr_b16 v[214:215], v170 offset:41600
	v_add_f32_e32 v173, v173, v194
	v_add_f32_e32 v174, v174, v195
	v_add_f32_e32 v173, v173, v196
	v_add_f32_e32 v174, v174, v197
	v_add_f32_e32 v173, v173, v198
	v_add_f32_e32 v174, v174, v199
	v_cvt_pk_bf16_f32 v184, v192, v193
	v_cvt_pk_bf16_f32 v185, v194, v195
	v_cvt_pk_bf16_f32 v186, v196, v197
	v_cvt_pk_bf16_f32 v187, v198, v199
	s_waitcnt lgkmcnt(2)
	v_mfma_f32_32x32x16_bf16 v[18:33], v[180:183], v[236:239], v[18:33]
	ds_read_b64_tr_b16 v[216:217], v170 offset:40512
	ds_read_b64_tr_b16 v[218:219], v170 offset:41664
	v_exp_f32_e32 v192, v90
	v_exp_f32_e32 v193, v91
	v_exp_f32_e32 v194, v92
	v_exp_f32_e32 v195, v93
	v_exp_f32_e32 v196, v94
	v_exp_f32_e32 v197, v95
	v_exp_f32_e32 v198, v96
	v_exp_f32_e32 v199, v97
	v_add_f32_e32 v173, v173, v192
	v_add_f32_e32 v174, v174, v193
	s_waitcnt lgkmcnt(2)
	v_mfma_f32_32x32x16_bf16 v[2:17], v[184:187], v[212:215], v[2:17]
	ds_read_b64_tr_b16 v[220:221], v170 offset:42752
	ds_read_b64_tr_b16 v[222:223], v170 offset:43904
	v_add_f32_e32 v173, v173, v194
	v_add_f32_e32 v174, v174, v195
	v_add_f32_e32 v173, v173, v196
	v_add_f32_e32 v174, v174, v197
	v_add_f32_e32 v173, v173, v198
	v_add_f32_e32 v174, v174, v199
	v_cvt_pk_bf16_f32 v188, v192, v193
	v_cvt_pk_bf16_f32 v189, v194, v195
	v_cvt_pk_bf16_f32 v190, v196, v197
	v_cvt_pk_bf16_f32 v191, v198, v199
	s_waitcnt lgkmcnt(2)
	v_mfma_f32_32x32x16_bf16 v[18:33], v[184:187], v[216:219], v[18:33]
	ds_read_b64_tr_b16 v[236:237], v170 offset:42816
	ds_read_b64_tr_b16 v[238:239], v170 offset:43968
	v_add_f32_e32 v172, v172, v173
	v_add_f32_e32 v172, v172, v174
	s_waitcnt lgkmcnt(2)
	v_mfma_f32_32x32x16_bf16 v[2:17], v[188:191], v[220:223], v[2:17]
	s_waitcnt lgkmcnt(0)
	v_mfma_f32_32x32x16_bf16 v[18:33], v[188:191], v[236:239], v[18:33]
	s_waitcnt lgkmcnt(0)
	s_barrier

; #define wt16(p, v) wt16b(WSB, (p), (v))
; #define LAS __attribute__((address_space(3)))
; __device__ __forceinline__ void ssd_item(CArgs a, int layer, int item, LAS unsigned char* lds) {
;     ...
;         const int c = dir ? 15 - cc : cc; const int t0 = c * 128;
;         const float dtv = pdt;
;         if (tid < 128) v_dA[tid] = dtv * Aneg;
;         __syncthreads();
;         if (cc > 0) {
; #pragma unroll
;             for (int i = 0; i < 2; ++i) { const int c2 = tid + 512 * i, row = c2 >> 3, part = c2 & 7;
;                 wt16(yout + (size_t)(tprev + row) * ystr + part * 8, *(const LAS u32x4*)(Bw + row * YS_LD + part * 8)); }
;         }
.LBB0_196:
	s_waitcnt vmcnt(20)
	v_mov_b32_e32 v123, v244
	s_nop 0
	v_readfirstlane_b32 s34, v123
	v_cmp_gt_i32_e32 vcc, s33, v123
	s_and_saveexec_b64 s[2:3], vcc
	v_lshl_add_u32 v18, v123, 2, 0
	v_mul_f32_e32 v0, v191, v192
	v_add_u32_e32 v18, 0x22000, v18
	ds_write_b32 v18, v0
	s_or_b64 exec, exec, s[2:3]
	s_cmp_eq_u32 s90, 0
	s_waitcnt lgkmcnt(0)
	s_barrier
	s_cbranch_scc1 .LBB0_200
	v_ashrrev_i32_e32 v18, 3, v123
	v_lshlrev_b32_e32 v0, 4, v123
	v_add_u32_e32 v19, s27, v18
	v_and_b32_e32 v22, 0x70, v0
	v_lshlrev_b32_e32 v19, s12, v19
	v_add_u32_e32 v0, 0, v22
	v_lshlrev_b32_e32 v19, 1, v19
	v_add3_u32 v23, s13, v19, v22
	v_mad_u64_u32 v[18:19], s[2:3], v18, s82, v[0:1]
	ds_read_b128 v[18:21], v18 offset:34816
	v_subrev_u32_e32 v23, s60, v23
	s_waitcnt lgkmcnt(0)
	buffer_store_dwordx4 v[18:21], v23, s[60:63], 0 offen sc1
	s_nop 1
	v_add_u32_e32 v18, 0x200, v123
	v_ashrrev_i32_e32 v18, 3, v18
	v_add_u32_e32 v19, s27, v18
	v_lshlrev_b32_e32 v19, s12, v19
	v_lshlrev_b32_e32 v19, 1, v19
	v_add3_u32 v22, s13, v19, v22
	v_mad_u64_u32 v[18:19], s[2:3], v18, s82, v[0:1]
	ds_read_b128 v[18:21], v18 offset:34816
	v_subrev_u32_e32 v0, s60, v22
	s_waitcnt lgkmcnt(0)
	buffer_store_dwordx4 v[18:21], v0, s[60:63], 0 offen sc1

; __device__ __forceinline__ unsigned cvt_pk_bf16(float lo, float hi) { f32x2_t v = {lo, hi}; bf16x2_t b = __builtin_convertvector(v, bf16x2_t); return __builtin_bit_cast(unsigned, b); }
; #define LAS __attribute__((address_space(3)))
; __device__ __forceinline__ float silu_f(float x) { return x * __builtin_amdgcn_rcpf(1.f + __expf(-x)); }
; __device__ __forceinline__ void ssd_item(CArgs a, int layer, int item, LAS unsigned char* lds) {
;     ...
;         etot = vec[640];
;         {
;             const int cg8 = tid & 15, rb = tid >> 4, l0 = rb * 4;
;             float o[4][8];
;             float wg[4];
; #pragma unroll
;             for (int r = 0; r < 4; ++r) { *(LAS u32x4*)(Cm + (l0 + r) * SS_LD + cg8 * 8) = pc[r]; *(LAS u32x4*)(Bw + (l0 + r) * SS_LD + cg8 * 8) = pb[r]; unpack8(pb[r], o[r]); wg[r] = v_wgt[l0 + r]; }
; #pragma unroll
;             for (int e = 0; e < 8; ++e) { u32x2 w; w.x = cvt_pk_bf16(o[0][e] * wg[0], o[1][e] * wg[1]); w.y = cvt_pk_bf16(o[2][e] * wg[2], o[3][e] * wg[3]);
;                 *(LAS u32x2*)(Bt + (cg8 * 8 + e) * SS_LD + l0) = w; }
;             const int xg = tid & 7, xr = tid >> 3, xl0 = xr * 2;
;             float ox[2][8];
;             {
;                 const int c0 = hd * 64 + xg * 8;
;                 float bias[8];
;                 { const f32x4 a0 = *(const f32x4*)(cb + c0), a1 = *(const f32x4*)(cb + c0 + 4);
;                   bias[0] = a0[0]; bias[1] = a0[1]; bias[2] = a0[2]; bias[3] = a0[3]; bias[4] = a1[0]; bias[5] = a1[1]; bias[6] = a1[2]; bias[7] = a1[3]; }
; #pragma unroll
;                 for (int e = 0; e < 8; ++e) { ox[0][e] = bias[e]; ox[1][e] = bias[e]; }
; #pragma unroll
;                 for (int k = 0; k < 5; ++k) {
;                     const f32x4 a0 = *(const f32x4*)(cw + k * 1536 + c0), a1 = *(const f32x4*)(cw + k * 1536 + c0 + 4);
;                     const float w[8] = {a0[0], a0[1], a0[2], a0[3], a1[0], a1[1], a1[2], a1[3]};
;                     float i0[8], i1[8]; unpack8(px[k], i0); unpack8(px[k + 1], i1);
; #pragma unroll
;                     for (int e = 0; e < 8; ++e) { ox[0][e] += w[e] * i0[e]; ox[1][e] += w[e] * i1[e]; }
;                 }
; #pragma unroll
;                 for (int e = 0; e < 8; ++e) { ox[0][e] = silu_f(ox[0][e]); ox[1][e] = silu_f(ox[1][e]); }
.LBB0_203:
	s_or_b64 exec, exec, s[26:27]
	v_lshlrev_b32_e32 v28, 3, v123
	v_mov_b32_e32 v0, s76
	v_ashrrev_i32_e32 v127, 2, v123
	v_and_b32_e32 v26, 0x78, v28
	s_waitcnt lgkmcnt(0)
	s_barrier
	ds_read_b32 v122, v0
	v_and_b32_e32 v22, -4, v127
	v_lshl_add_u32 v0, v26, 1, 0
	v_mad_u64_u32 v[18:19], s[2:3], v22, s84, v[0:1]
	s_add_i32 s26, 0, 0x22600
	s_waitcnt vmcnt(14)
	ds_write_b128 v18, v[54:57]
	ds_write_b128 v18, v[50:53] offset:34816
	v_lshl_add_u32 v19, v22, 2, s26
	v_or_b32_e32 v23, 3, v127
	v_lshlrev_b32_e32 v27, 1, v22
	ds_read_b32 v22, v19
	ds_write_b128 v18, v[62:65] offset:272
	ds_write_b128 v18, v[58:61] offset:35088
	v_mad_u64_u32 v[20:21], s[2:3], v23, s84, v[0:1]
	v_lshl_add_u32 v0, v23, 2, s26
	ds_read_b32 v23, v19 offset:4
	ds_write_b128 v18, v[70:73] offset:544
	ds_write_b128 v18, v[66:69] offset:35360
	ds_read_b32 v18, v19 offset:8
	ds_write_b128 v20, v[78:81]
	ds_write_b128 v20, v[74:77] offset:34816
	ds_read_b32 v19, v0
	v_lshlrev_b32_e32 v25, 16, v58
	v_lshlrev_b32_e32 v24, 16, v50
	s_waitcnt lgkmcnt(6)
	v_pk_mul_f32 v[20:21], v[22:23], v[24:25]
	v_lshlrev_b32_e32 v25, 16, v74
	v_lshlrev_b32_e32 v24, 16, v66
	s_waitcnt lgkmcnt(0)
	v_pk_mul_f32 v[24:25], v[18:19], v[24:25]
	v_mul_u32_u24_e32 v0, 0x110, v26
	v_cvt_pk_bf16_f32 v20, v20, v21
	v_cvt_pk_bf16_f32 v21, v24, v25
	v_add3_u32 v0, s77, v27, v0
	v_and_b32_e32 v25, 0xffff0000, v58
	v_and_b32_e32 v24, 0xffff0000, v50
	v_and_b32_e32 v27, 0xffff0000, v74
	v_and_b32_e32 v26, 0xffff0000, v66
	v_pk_mul_f32 v[24:25], v[22:23], v[24:25]
	v_pk_mul_f32 v[26:27], v[18:19], v[26:27]
	v_cvt_pk_bf16_f32 v24, v24, v25
	v_cvt_pk_bf16_f32 v25, v26, v27
	ds_write2_b64 v0, v[20:21], v[24:25] offset1:34
	v_lshlrev_b32_e32 v21, 16, v59
	v_lshlrev_b32_e32 v20, 16, v51
	v_lshlrev_b32_e32 v25, 16, v75
	v_lshlrev_b32_e32 v24, 16, v67
	v_pk_mul_f32 v[20:21], v[22:23], v[20:21]
	v_pk_mul_f32 v[24:25], v[18:19], v[24:25]
	v_cvt_pk_bf16_f32 v20, v20, v21
	v_cvt_pk_bf16_f32 v21, v24, v25
	v_and_b32_e32 v25, 0xffff0000, v59
	v_and_b32_e32 v24, 0xffff0000, v51
	v_and_b32_e32 v27, 0xffff0000, v75
	v_and_b32_e32 v26, 0xffff0000, v67
	v_pk_mul_f32 v[24:25], v[22:23], v[24:25]
	v_pk_mul_f32 v[26:27], v[18:19], v[26:27]
	v_cvt_pk_bf16_f32 v24, v24, v25
	v_cvt_pk_bf16_f32 v25, v26, v27
	ds_write2_b64 v0, v[20:21], v[24:25] offset0:68 offset1:102
	v_lshlrev_b32_e32 v21, 16, v60
	v_lshlrev_b32_e32 v20, 16, v52
	v_lshlrev_b32_e32 v25, 16, v76
	v_lshlrev_b32_e32 v24, 16, v68
	v_pk_mul_f32 v[20:21], v[22:23], v[20:21]
	v_pk_mul_f32 v[24:25], v[18:19], v[24:25]
	v_cvt_pk_bf16_f32 v20, v20, v21
	v_cvt_pk_bf16_f32 v21, v24, v25
	v_and_b32_e32 v25, 0xffff0000, v60
	v_and_b32_e32 v24, 0xffff0000, v52
	v_and_b32_e32 v27, 0xffff0000, v76
	v_and_b32_e32 v26, 0xffff0000, v68
	v_pk_mul_f32 v[24:25], v[22:23], v[24:25]
	v_pk_mul_f32 v[26:27], v[18:19], v[26:27]
	v_cvt_pk_bf16_f32 v24, v24, v25
	v_cvt_pk_bf16_f32 v25, v26, v27
	ds_write2_b64 v0, v[20:21], v[24:25] offset0:136 offset1:170
	v_lshlrev_b32_e32 v21, 16, v61
	v_lshlrev_b32_e32 v20, 16, v53
	v_lshlrev_b32_e32 v25, 16, v77
	v_lshlrev_b32_e32 v24, 16, v69
	v_pk_mul_f32 v[20:21], v[22:23], v[20:21]
	v_pk_mul_f32 v[24:25], v[18:19], v[24:25]
	v_cvt_pk_bf16_f32 v20, v20, v21
	v_cvt_pk_bf16_f32 v21, v24, v25
	v_and_b32_e32 v25, 0xffff0000, v61
	v_and_b32_e32 v24, 0xffff0000, v53
	v_pk_mul_f32 v[22:23], v[22:23], v[24:25]
	v_and_b32_e32 v25, 0xffff0000, v77
	v_and_b32_e32 v24, 0xffff0000, v69
	v_pk_mul_f32 v[18:19], v[18:19], v[24:25]
	v_cvt_pk_bf16_f32 v22, v22, v23
	v_cvt_pk_bf16_f32 v23, v18, v19
	v_and_b32_e32 v128, 56, v28
	ds_write2_b64 v0, v[20:21], v[22:23] offset0:204 offset1:238
	v_or_b32_e32 v0, s89, v128
	v_lshlrev_b32_e32 v0, 2, v0
	v_lshl_add_u64 v[38:39], s[18:19], 0, v[0:1]
	v_add_co_u32_e32 v28, vcc, s74, v38
	global_load_dwordx4 v[18:21], v0, s[20:21] offset:16
	global_load_dwordx4 v[42:45], v0, s[20:21]
	v_addc_co_u32_e32 v29, vcc, 0, v39, vcc
	v_add_co_u32_e32 v32, vcc, s97, v38
	global_load_dwordx4 v[22:25], v0, s[18:19] offset:16
	global_load_dwordx4 v[46:49], v0, s[18:19]
	v_addc_co_u32_e32 v33, vcc, 0, v39, vcc
	v_lshl_add_u64 v[26:27], v[38:39], 0, s[68:69]
	v_add_co_u32_e32 v36, vcc, s65, v38
	global_load_dwordx4 v[106:109], v[28:29], off offset:2048
	s_nop 0
	global_load_dwordx4 v[26:29], v[26:27], off offset:16
	v_lshl_add_u64 v[30:31], v[38:39], 0, s[86:87]
	v_addc_co_u32_e32 v37, vcc, 0, v39, vcc
	global_load_dwordx4 v[110:113], v[32:33], off
	s_nop 0
	global_load_dwordx4 v[30:33], v[30:31], off offset:16
	v_lshl_add_u64 v[34:35], v[38:39], 0, s[72:73]
	v_lshl_add_u64 v[40:41], v[38:39], 0, s[0:1]
	v_add_co_u32_e32 v38, vcc, s95, v38
	global_load_dwordx4 v[114:117], v[36:37], off offset:2048
	s_nop 0
	global_load_dwordx4 v[34:37], v[34:35], off offset:16
	v_addc_co_u32_e32 v39, vcc, 0, v39, vcc
	global_load_dwordx4 v[118:121], v[38:39], off
	s_nop 0
	global_load_dwordx4 v[38:41], v[40:41], off offset:16
	s_waitcnt vmcnt(14)
	v_lshlrev_b32_e32 v124, 16, v84
	v_lshlrev_b32_e32 v125, 16, v88
	v_lshlrev_b32_e32 v131, 16, v92
	v_mov_b32_e32 v130, v125
	v_lshlrev_b32_e32 v133, 16, v96
	v_mov_b32_e32 v132, v131
	v_lshlrev_b32_e32 v135, 16, v100
	v_mov_b32_e32 v134, v133
	s_add_i32 s26, s90, 1
	s_cmp_eq_u32 s10, -1
	s_waitcnt vmcnt(8)
	v_pk_fma_f32 v[124:125], v[46:47], v[124:125], v[42:43] op_sel_hi:[0,1,0]
	s_waitcnt vmcnt(7)
	v_pk_fma_f32 v[124:125], v[106:107], v[130:131], v[124:125] op_sel_hi:[0,1,1]
	v_lshlrev_b32_e32 v131, 16, v104
	v_mov_b32_e32 v130, v135
	s_waitcnt vmcnt(5)
	v_pk_fma_f32 v[124:125], v[110:111], v[132:133], v[124:125] op_sel_hi:[0,1,1]
	v_and_b32_e32 v133, 0xffff0000, v92
	s_waitcnt vmcnt(3)
; __device__ __forceinline__ float silu_f(float x) { return x * __builtin_amdgcn_rcpf(1.f + __expf(-x)); }
; __device__ __forceinline__ void ssd_item(CArgs a, int layer, int item, LAS unsigned char* lds) {
;     ...
;             {
;                 const int c0 = hd * 64 + xg * 8;
;                 float bias[8];
;                 { const f32x4 a0 = *(const f32x4*)(cb + c0), a1 = *(const f32x4*)(cb + c0 + 4);
;                   bias[0] = a0[0]; bias[1] = a0[1]; bias[2] = a0[2]; bias[3] = a0[3]; bias[4] = a1[0]; bias[5] = a1[1]; bias[6] = a1[2]; bias[7] = a1[3]; }
; #pragma unroll
;                 for (int e = 0; e < 8; ++e) { ox[0][e] = bias[e]; ox[1][e] = bias[e]; }
; #pragma unroll
;                 for (int k = 0; k < 5; ++k) {
;                     const f32x4 a0 = *(const f32x4*)(cw + k * 1536 + c0), a1 = *(const f32x4*)(cw + k * 1536 + c0 + 4);
;                     const float w[8] = {a0[0], a0[1], a0[2], a0[3], a1[0], a1[1], a1[2], a1[3]};
;                     float i0[8], i1[8]; unpack8(px[k], i0); unpack8(px[k + 1], i1);
; #pragma unroll
;                     for (int e = 0; e < 8; ++e) { ox[0][e] += w[e] * i0[e]; ox[1][e] += w[e] * i1[e]; }
;                 }
; #pragma unroll
;                 for (int e = 0; e < 8; ++e) { ox[0][e] = silu_f(ox[0][e]); ox[1][e] = silu_f(ox[1][e]); }
	v_pk_fma_f32 v[124:125], v[114:115], v[134:135], v[124:125] op_sel_hi:[0,1,1]
	v_and_b32_e32 v135, 0xffff0000, v96
	v_mov_b32_e32 v134, v133
	s_waitcnt vmcnt(1)
	v_pk_fma_f32 v[124:125], v[118:119], v[130:131], v[124:125] op_sel_hi:[0,1,1]
	v_mul_f32_e32 v0, 0xbfb8aa3b, v124
	v_exp_f32_e32 v0, v0
	s_nop 0
	v_add_f32_e32 v0, 1.0, v0
	v_rcp_f32_e32 v130, v0
	v_mul_f32_e32 v0, 0xbfb8aa3b, v125
	v_exp_f32_e32 v0, v0
	s_nop 0
	v_add_f32_e32 v0, 1.0, v0
	v_rcp_f32_e32 v131, v0
	s_nop 0
	v_pk_mul_f32 v[124:125], v[124:125], v[130:131]
	v_and_b32_e32 v131, 0xffff0000, v88
	v_and_b32_e32 v130, 0xffff0000, v84
	v_mov_b32_e32 v132, v131
	v_pk_fma_f32 v[42:43], v[46:47], v[130:131], v[42:43] op_sel:[1,0,1]
	v_and_b32_e32 v47, 0xffff0000, v100
	v_pk_fma_f32 v[42:43], v[106:107], v[132:133], v[42:43] op_sel:[1,0,0]
	v_mov_b32_e32 v46, v135
	v_pk_fma_f32 v[42:43], v[110:111], v[134:135], v[42:43] op_sel:[1,0,0]
	v_and_b32_e32 v107, 0xffff0000, v104
	v_mov_b32_e32 v106, v47
	v_pk_fma_f32 v[42:43], v[114:115], v[46:47], v[42:43] op_sel:[1,0,0]
	v_lshlrev_b32_e32 v111, 16, v97
	v_pk_fma_f32 v[42:43], v[118:119], v[106:107], v[42:43] op_sel:[1,0,0]
	v_lshlrev_b32_e32 v107, 16, v93
	v_mul_f32_e32 v0, 0xbfb8aa3b, v42
	v_exp_f32_e32 v0, v0
	v_mov_b32_e32 v110, v107
	v_lshlrev_b32_e32 v115, 16, v101
	v_mov_b32_e32 v114, v111
	v_add_f32_e32 v0, 1.0, v0
	v_rcp_f32_e32 v46, v0
	v_mul_f32_e32 v0, 0xbfb8aa3b, v43
	v_exp_f32_e32 v0, v0
	s_nop 0
	v_add_f32_e32 v0, 1.0, v0
	v_rcp_f32_e32 v47, v0
	s_nop 0
	v_pk_mul_f32 v[42:43], v[42:43], v[46:47]
	v_lshlrev_b32_e32 v46, 16, v85
	v_lshlrev_b32_e32 v47, 16, v89
	v_mov_b32_e32 v106, v47
	v_pk_fma_f32 v[46:47], v[48:49], v[46:47], v[44:45] op_sel_hi:[0,1,0]
	v_pk_fma_f32 v[46:47], v[108:109], v[106:107], v[46:47] op_sel_hi:[0,1,1]
	v_pk_fma_f32 v[46:47], v[112:113], v[110:111], v[46:47] op_sel_hi:[0,1,1]
	v_lshlrev_b32_e32 v107, 16, v105
	v_mov_b32_e32 v106, v115
	v_pk_fma_f32 v[46:47], v[116:117], v[114:115], v[46:47] op_sel_hi:[0,1,1]
	v_pk_fma_f32 v[46:47], v[120:121], v[106:107], v[46:47] op_sel_hi:[0,1,1]
	v_mul_f32_e32 v0, 0xbfb8aa3b, v46
	v_exp_f32_e32 v0, v0
	v_mov_b32_e32 v44, v45
	v_and_b32_e32 v111, 0xffff0000, v93
	v_and_b32_e32 v115, 0xffff0000, v97
	v_add_f32_e32 v0, 1.0, v0
	v_rcp_f32_e32 v106, v0
	v_mul_f32_e32 v0, 0xbfb8aa3b, v47
	v_exp_f32_e32 v0, v0
	v_mov_b32_e32 v114, v111
	v_mov_b32_e32 v48, v115
	v_add_f32_e32 v0, 1.0, v0
	v_rcp_f32_e32 v107, v0
	v_mov_b32_e32 v0, v49
	v_and_b32_e32 v49, 0xffff0000, v101
	v_pk_mul_f32 v[46:47], v[46:47], v[106:107]
	v_and_b32_e32 v107, 0xffff0000, v89
	v_and_b32_e32 v106, 0xffff0000, v85
	v_mov_b32_e32 v110, v107
	v_pk_fma_f32 v[44:45], v[0:1], v[106:107], v[44:45] op_sel_hi:[0,1,0]
	v_mov_b32_e32 v0, v109
	v_pk_fma_f32 v[44:45], v[0:1], v[110:111], v[44:45] op_sel_hi:[0,1,1]
	v_mov_b32_e32 v0, v113
	v_pk_fma_f32 v[44:45], v[0:1], v[114:115], v[44:45] op_sel_hi:[0,1,1]
	v_mov_b32_e32 v0, v117
	v_and_b32_e32 v107, 0xffff0000, v105
	v_mov_b32_e32 v106, v49
	v_pk_fma_f32 v[44:45], v[0:1], v[48:49], v[44:45] op_sel_hi:[0,1,1]
	v_mov_b32_e32 v0, v121
	v_pk_fma_f32 v[44:45], v[0:1], v[106:107], v[44:45] op_sel_hi:[0,1,1]
	v_mul_f32_e32 v0, 0xbfb8aa3b, v44
	v_exp_f32_e32 v0, v0
	v_lshlrev_b32_e32 v107, 16, v90
	v_lshlrev_b32_e32 v109, 16, v94
	v_mov_b32_e32 v108, v107
	v_add_f32_e32 v0, 1.0, v0
	v_rcp_f32_e32 v48, v0
	v_mul_f32_e32 v0, 0xbfb8aa3b, v45
	v_exp_f32_e32 v0, v0
	v_lshlrev_b32_e32 v111, 16, v98
	v_mov_b32_e32 v110, v109
	v_add_f32_e32 v0, 1.0, v0
	v_rcp_f32_e32 v49, v0
	s_nop 0
	v_pk_mul_f32 v[44:45], v[44:45], v[48:49]
	v_lshlrev_b32_e32 v48, 16, v82
	v_lshlrev_b32_e32 v49, 16, v86
	v_mov_b32_e32 v106, v49
	v_pk_fma_f32 v[48:49], v[22:23], v[48:49], v[18:19] op_sel_hi:[0,1,0]
	v_pk_fma_f32 v[48:49], v[26:27], v[106:107], v[48:49] op_sel_hi:[0,1,1]
	v_pk_fma_f32 v[48:49], v[30:31], v[108:109], v[48:49] op_sel_hi:[0,1,1]
	v_lshlrev_b32_e32 v107, 16, v102
	v_mov_b32_e32 v106, v111
	v_pk_fma_f32 v[48:49], v[34:35], v[110:111], v[48:49] op_sel_hi:[0,1,1]
	s_waitcnt vmcnt(0)
	v_pk_fma_f32 v[48:49], v[38:39], v[106:107], v[48:49] op_sel_hi:[0,1,1]
	v_mul_f32_e32 v0, 0xbfb8aa3b, v48
	v_exp_f32_e32 v0, v0
	v_and_b32_e32 v109, 0xffff0000, v90
	v_and_b32_e32 v111, 0xffff0000, v94
	v_mov_b32_e32 v110, v109
	v_add_f32_e32 v0, 1.0, v0
	v_rcp_f32_e32 v106, v0
	v_mul_f32_e32 v0, 0xbfb8aa3b, v49
	v_exp_f32_e32 v0, v0
	s_nop 0
	v_add_f32_e32 v0, 1.0, v0
	v_rcp_f32_e32 v107, v0
	s_nop 0
	v_pk_mul_f32 v[48:49], v[48:49], v[106:107]
	v_and_b32_e32 v107, 0xffff0000, v86
	v_and_b32_e32 v106, 0xffff0000, v82
	v_mov_b32_e32 v108, v107
	v_pk_fma_f32 v[18:19], v[22:23], v[106:107], v[18:19] op_sel:[1,0,1]
	v_and_b32_e32 v23, 0xffff0000, v98
	v_pk_fma_f32 v[18:19], v[26:27], v[108:109], v[18:19] op_sel:[1,0,0]
	v_mov_b32_e32 v22, v111
	v_pk_fma_f32 v[18:19], v[30:31], v[110:111], v[18:19] op_sel:[1,0,0]
	v_and_b32_e32 v27, 0xffff0000, v102
	v_mov_b32_e32 v26, v23
	v_pk_fma_f32 v[18:19], v[34:35], v[22:23], v[18:19] op_sel:[1,0,0]
	v_lshlrev_b32_e32 v31, 16, v95
	v_pk_fma_f32 v[18:19], v[38:39], v[26:27], v[18:19] op_sel:[1,0,0]
	v_lshlrev_b32_e32 v27, 16, v91
	v_mul_f32_e32 v0, 0xbfb8aa3b, v18
	v_exp_f32_e32 v0, v0
	v_mov_b32_e32 v30, v27
	v_lshlrev_b32_e32 v35, 16, v99
	v_mov_b32_e32 v34, v31
	v_add_f32_e32 v0, 1.0, v0
	v_rcp_f32_e32 v22, v0
	v_mul_f32_e32 v0, 0xbfb8aa3b, v19
	v_exp_f32_e32 v0, v0
	s_nop 0
	v_add_f32_e32 v0, 1.0, v0
	v_rcp_f32_e32 v23, v0
	s_nop 0
	v_pk_mul_f32 v[18:19], v[18:19], v[22:23]
	v_lshlrev_b32_e32 v22, 16, v83
	v_lshlrev_b32_e32 v23, 16, v87
	v_mov_b32_e32 v26, v23
	v_pk_fma_f32 v[22:23], v[24:25], v[22:23], v[20:21] op_sel_hi:[0,1,0]
; __device__ __forceinline__ unsigned cvt_pk_bf16(float lo, float hi) { f32x2_t v = {lo, hi}; bf16x2_t b = __builtin_convertvector(v, bf16x2_t); return __builtin_bit_cast(unsigned, b); }
; #define LAS __attribute__((address_space(3)))
; __device__ __forceinline__ float silu_f(float x) { return x * __builtin_amdgcn_rcpf(1.f + __expf(-x)); }
; __device__ __forceinline__ void ssd_item(CArgs a, int layer, int item, LAS unsigned char* lds) {
;     ...
;                 for (int e = 0; e < 8; ++e) { ox[0][e] = silu_f(ox[0][e]); ox[1][e] = silu_f(ox[1][e]); }
;             }
; #pragma unroll
;             for (int e = 0; e < 8; ++e) *(LAS unsigned*)(Xt + (xg * 8 + e) * SS_LD + xl0) = cvt_pk_bf16(ox[0][e], ox[1][e]);
;         }
;         if (cc + 1 < 16) SSD_PREFETCH(cc + 1);
	v_pk_fma_f32 v[22:23], v[28:29], v[26:27], v[22:23] op_sel_hi:[0,1,1]
	v_pk_fma_f32 v[22:23], v[32:33], v[30:31], v[22:23] op_sel_hi:[0,1,1]
	v_lshlrev_b32_e32 v27, 16, v103
	v_mov_b32_e32 v26, v35
	v_pk_fma_f32 v[22:23], v[36:37], v[34:35], v[22:23] op_sel_hi:[0,1,1]
	v_pk_fma_f32 v[22:23], v[40:41], v[26:27], v[22:23] op_sel_hi:[0,1,1]
	v_mul_f32_e32 v0, 0xbfb8aa3b, v22
	v_exp_f32_e32 v0, v0
	v_mov_b32_e32 v20, v21
	v_and_b32_e32 v31, 0xffff0000, v91
	v_and_b32_e32 v35, 0xffff0000, v95
	v_add_f32_e32 v0, 1.0, v0
	v_rcp_f32_e32 v26, v0
	v_mul_f32_e32 v0, 0xbfb8aa3b, v23
	v_exp_f32_e32 v0, v0
	v_mov_b32_e32 v34, v31
	v_mov_b32_e32 v24, v35
	v_cvt_pk_bf16_f32 v18, v18, v19
	v_add_f32_e32 v0, 1.0, v0
	v_rcp_f32_e32 v27, v0
	v_mov_b32_e32 v0, v25
	v_and_b32_e32 v25, 0xffff0000, v99
	v_pk_mul_f32 v[22:23], v[22:23], v[26:27]
	v_and_b32_e32 v27, 0xffff0000, v87
	v_and_b32_e32 v26, 0xffff0000, v83
	v_mov_b32_e32 v30, v27
	v_pk_fma_f32 v[20:21], v[0:1], v[26:27], v[20:21] op_sel_hi:[0,1,0]
	v_mov_b32_e32 v0, v29
	v_pk_fma_f32 v[20:21], v[0:1], v[30:31], v[20:21] op_sel_hi:[0,1,1]
	v_mov_b32_e32 v0, v33
	v_pk_fma_f32 v[20:21], v[0:1], v[34:35], v[20:21] op_sel_hi:[0,1,1]
	v_mov_b32_e32 v0, v37
	v_and_b32_e32 v27, 0xffff0000, v103
	v_mov_b32_e32 v26, v25
	v_pk_fma_f32 v[20:21], v[0:1], v[24:25], v[20:21] op_sel_hi:[0,1,1]
	v_mov_b32_e32 v0, v41
	v_pk_fma_f32 v[20:21], v[0:1], v[26:27], v[20:21] op_sel_hi:[0,1,1]
	v_mul_f32_e32 v0, 0xbfb8aa3b, v20
	v_exp_f32_e32 v0, v0
	s_nop 0
	v_add_f32_e32 v0, 1.0, v0
	v_rcp_f32_e32 v24, v0
	v_mul_f32_e32 v0, 0xbfb8aa3b, v21
	v_exp_f32_e32 v0, v0
	s_nop 0
	v_add_f32_e32 v0, 1.0, v0
	v_rcp_f32_e32 v25, v0
	v_lshlrev_b32_e32 v0, 1, v127
	v_and_b32_e32 v0, -4, v0
	v_pk_mul_f32 v[20:21], v[20:21], v[24:25]
	v_mul_u32_u24_e32 v25, 0x110, v128
	v_cvt_pk_bf16_f32 v24, v124, v125
	v_add3_u32 v0, s38, v0, v25
	v_cvt_pk_bf16_f32 v25, v42, v43
	ds_write2_b32 v0, v24, v25 offset1:68
	v_cvt_pk_bf16_f32 v24, v46, v47
	v_cvt_pk_bf16_f32 v25, v44, v45
	ds_write2_b32 v0, v24, v25 offset0:136 offset1:204
	v_cvt_pk_bf16_f32 v24, v48, v49
	v_add_u32_e32 v0, 0x400, v0
	ds_write2_b32 v0, v24, v18 offset0:16 offset1:84
	v_cvt_pk_bf16_f32 v18, v22, v23
	v_cvt_pk_bf16_f32 v19, v20, v21
	ds_write2_b32 v0, v18, v19 offset0:152 offset1:220
	s_cbranch_scc1 .LBB0_207
	s_cmp_eq_u32 s10, 0
	s_cbranch_scc1 .Lssd_pf_slow
	v_mov_b32_e32 v42, v244
	s_and_b64 s[2:3], s[40:41], exec
	s_cselect_b32 s2, s26, s10
	v_ashrrev_i32_e32 v20, 2, v42
	s_lshl_b32 s27, s2, 7
	v_mov_b32_e32 v192, 0
	v_readfirstlane_b32 s3, v244
	s_cmp_lt_u32 s3, 0x80
	s_cbranch_scc0 .Lssd_nopdt
	v_add_u32_e32 v220, s27, v244
	v_lshlrev_b32_e32 v220, 7, v220
	global_load_dword v192, v220, s[16:17]
.Lssd_nopdt:
	v_and_b32_e32 v0, -4, v20
	v_add_u32_e32 v18, s27, v0
	v_ashrrev_i32_e32 v19, 31, v18
	v_lshlrev_b64 v[18:19], 10, v[18:19]
	v_lshlrev_b32_e32 v21, 4, v42
	v_lshl_add_u64 v[18:19], s[22:23], 0, v[18:19]
	v_and_b32_e32 v0, 0xf0, v21
	v_lshl_add_u64 v[18:19], v[18:19], 0, v[0:1]
	v_and_b32_e32 v0, -2, v20
	global_load_dwordx4 v[50:53], v[18:19], off
	global_load_dwordx4 v[54:57], v[18:19], off offset:512
	global_load_dwordx4 v[58:61], v[18:19], off offset:1024
	global_load_dwordx4 v[62:65], v[18:19], off offset:1536
	global_load_dwordx4 v[66:69], v[18:19], off offset:2048
	global_load_dwordx4 v[70:73], v[18:19], off offset:2560
	global_load_dwordx4 v[74:77], v[18:19], off offset:3072
	global_load_dwordx4 v[78:81], v[18:19], off offset:3584
	v_add_u32_e32 v38, s27, v0
	v_add_u32_e32 v22, -2, v38
	v_add_u32_e32 v26, -1, v38
	v_or_b32_e32 v34, 1, v38
	v_add_u32_e32 v39, 2, v38
	v_add_u32_e32 v43, 3, v38
	v_med3_i32 v23, v22, 0, v248
	v_med3_i32 v27, v26, 0, v248
	v_med3_i32 v30, v38, 0, v248
	v_med3_i32 v35, v34, 0, v248
	v_med3_i32 v40, v39, 0, v248
	v_med3_i32 v44, v43, 0, v248
	v_mul_u32_u24_e32 v0, 0x1200, v23
	v_cmp_eq_u32_e32 vcc, v22, v23
	v_mul_u32_u24_e32 v22, 0x1200, v27
	v_mov_b32_e32 v23, v1
	v_cmp_eq_u32_e64 s[42:43], v26, v27
	v_mul_u32_u24_e32 v26, 0x1200, v30
	v_mov_b32_e32 v27, v1
	v_cmp_eq_u32_e64 s[44:45], v38, v30
	v_mul_u32_u24_e32 v30, 0x1200, v35
	v_mov_b32_e32 v31, v1
	v_cmp_eq_u32_e64 s[46:47], v34, v35
	v_mul_u32_u24_e32 v34, 0x1200, v40
	v_mov_b32_e32 v35, v1
	v_cmp_eq_u32_e64 s[48:49], v39, v40
	v_mul_u32_u24_e32 v38, 0x1200, v44
	v_mov_b32_e32 v39, v1
	v_lshl_add_u64 v[18:19], v[0:1], 1, s[24:25]
	v_and_b32_e32 v0, 0x70, v21
	v_lshl_add_u64 v[22:23], v[22:23], 1, s[24:25]
	v_lshl_add_u64 v[26:27], v[26:27], 1, s[24:25]
	v_lshl_add_u64 v[30:31], v[30:31], 1, s[24:25]
	v_lshl_add_u64 v[34:35], v[34:35], 1, s[24:25]
	v_lshl_add_u64 v[38:39], v[38:39], 1, s[24:25]
	v_lshl_add_u64 v[18:19], v[18:19], 0, v[0:1]
	v_lshl_add_u64 v[22:23], v[22:23], 0, v[0:1]
	v_lshl_add_u64 v[26:27], v[26:27], 0, v[0:1]
	v_lshl_add_u64 v[30:31], v[30:31], 0, v[0:1]
	v_lshl_add_u64 v[34:35], v[34:35], 0, v[0:1]
	v_lshl_add_u64 v[38:39], v[38:39], 0, v[0:1]
	global_load_dwordx2 v[84:85], v[18:19], off offset:2048
	global_load_dwordx2 v[82:83], v[18:19], off offset:2056
	v_cmp_eq_u32_e64 s[50:51], v43, v44
	global_load_dwordx2 v[88:89], v[22:23], off offset:2048
	global_load_dwordx2 v[86:87], v[22:23], off offset:2056
	v_cmp_gt_i32_e64 s[54:55], s33, v42
	global_load_dwordx2 v[92:93], v[26:27], off offset:2048
	global_load_dwordx2 v[90:91], v[26:27], off offset:2056
	global_load_dwordx2 v[96:97], v[30:31], off offset:2048
	global_load_dwordx2 v[94:95], v[30:31], off offset:2056
	s_nop 0
	global_load_dwordx2 v[100:101], v[34:35], off offset:2048
	global_load_dwordx2 v[98:99], v[34:35], off offset:2056
	s_nop 0
	global_load_dwordx2 v[104:105], v[38:39], off offset:2048
	global_load_dwordx2 v[102:103], v[38:39], off offset:2056
	s_branch .LBB0_207
.Lssd_pf_slow:
	v_mov_b32_e32 v42, v244
	s_and_b64 s[2:3], s[40:41], exec
	s_cselect_b32 s2, s26, s10
	v_ashrrev_i32_e32 v20, 2, v42
	s_lshl_b32 s27, s2, 7
	v_and_b32_e32 v0, -4, v20
	v_add_u32_e32 v18, s27, v0
	v_ashrrev_i32_e32 v19, 31, v18
	v_lshlrev_b64 v[18:19], 10, v[18:19]
	v_lshlrev_b32_e32 v21, 4, v42
	v_lshl_add_u64 v[18:19], s[22:23], 0, v[18:19]
	v_and_b32_e32 v0, 0xf0, v21
	v_lshl_add_u64 v[18:19], v[18:19], 0, v[0:1]
	v_and_b32_e32 v0, -2, v20
	global_load_dwordx4 v[50:53], v[18:19], off
	global_load_dwordx4 v[54:57], v[18:19], off offset:512
	global_load_dwordx4 v[58:61], v[18:19], off offset:1024
	global_load_dwordx4 v[62:65], v[18:19], off offset:1536
	global_load_dwordx4 v[66:69], v[18:19], off offset:2048
	global_load_dwordx4 v[70:73], v[18:19], off offset:2560
	global_load_dwordx4 v[74:77], v[18:19], off offset:3072
	global_load_dwordx4 v[78:81], v[18:19], off offset:3584
	v_add_u32_e32 v38, s27, v0
	v_add_u32_e32 v22, -2, v38
	v_add_u32_e32 v26, -1, v38
	v_or_b32_e32 v34, 1, v38
	v_add_u32_e32 v39, 2, v38
	v_add_u32_e32 v43, 3, v38
	v_med3_i32 v23, v22, 0, v248
	v_med3_i32 v27, v26, 0, v248
	v_med3_i32 v30, v38, 0, v248
	v_med3_i32 v35, v34, 0, v248
	v_med3_i32 v40, v39, 0, v248
	v_med3_i32 v44, v43, 0, v248
	v_mul_u32_u24_e32 v0, 0x1200, v23
	v_cmp_eq_u32_e32 vcc, v22, v23
	v_mul_u32_u24_e32 v22, 0x1200, v27
	v_mov_b32_e32 v23, v1
	v_cmp_eq_u32_e64 s[42:43], v26, v27
	v_mul_u32_u24_e32 v26, 0x1200, v30
	v_mov_b32_e32 v27, v1
	v_cmp_eq_u32_e64 s[44:45], v38, v30
	v_mul_u32_u24_e32 v30, 0x1200, v35
	v_mov_b32_e32 v31, v1
	v_cmp_eq_u32_e64 s[46:47], v34, v35
	v_mul_u32_u24_e32 v34, 0x1200, v40
	v_mov_b32_e32 v35, v1
	v_cmp_eq_u32_e64 s[48:49], v39, v40
	v_mul_u32_u24_e32 v38, 0x1200, v44
	v_mov_b32_e32 v39, v1
	v_lshl_add_u64 v[18:19], v[0:1], 1, s[24:25]
	v_and_b32_e32 v0, 0x70, v21
	v_lshl_add_u64 v[22:23], v[22:23], 1, s[24:25]
	v_lshl_add_u64 v[26:27], v[26:27], 1, s[24:25]
	v_lshl_add_u64 v[30:31], v[30:31], 1, s[24:25]
	v_lshl_add_u64 v[34:35], v[34:35], 1, s[24:25]
	v_lshl_add_u64 v[38:39], v[38:39], 1, s[24:25]
	v_lshl_add_u64 v[18:19], v[18:19], 0, v[0:1]
	v_lshl_add_u64 v[22:23], v[22:23], 0, v[0:1]
	v_lshl_add_u64 v[26:27], v[26:27], 0, v[0:1]
	v_lshl_add_u64 v[30:31], v[30:31], 0, v[0:1]
	v_lshl_add_u64 v[34:35], v[34:35], 0, v[0:1]
	v_lshl_add_u64 v[38:39], v[38:39], 0, v[0:1]
	global_load_dwordx4 v[18:21], v[18:19], off offset:2048
	v_cmp_eq_u32_e64 s[50:51], v43, v44
	global_load_dwordx4 v[22:25], v[22:23], off offset:2048
	v_cmp_gt_i32_e64 s[54:55], s33, v42
	global_load_dwordx4 v[26:29], v[26:27], off offset:2048
	v_mov_b32_e32 v192, 0
	global_load_dwordx4 v[30:33], v[30:31], off offset:2048
	s_nop 0
	global_load_dwordx4 v[34:37], v[34:35], off offset:2048
	s_nop 0
	global_load_dwordx4 v[38:41], v[38:39], off offset:2048
	s_and_saveexec_b64 s[2:3], s[54:55]
	s_cbranch_execz .LBB0_206
	v_add_u32_e32 v42, s27, v42
	v_ashrrev_i32_e32 v43, 31, v42
	v_lshlrev_b64 v[42:43], 7, v[42:43]
	v_lshl_add_u64 v[42:43], s[16:17], 0, v[42:43]
	global_load_dword v192, v[42:43], off
